# k35: static s_setprio 2 for the scan's elementwise E roles (waves 4-7) over the roles sharing their SIMDs
# baseline (speedup 1.0000x reference)
.LBB0_718:
	s_mov_b64 s[4:5], -1
	s_mov_b64 s[10:11], 0
	s_cmp_lt_i32 s70, 5
	s_mov_b64 s[46:47], 0
	s_barrier
	s_cbranch_scc1 .LBB0_770
	s_cmp_gt_i32 s70, 5
	s_cbranch_scc0 .LBB0_754
	s_cmp_gt_i32 s70, 6
	s_cbranch_scc0 .LBB0_738
	s_cmp_eq_u32 s70, 7
	s_mov_b64 s[46:47], -1
	s_cbranch_scc0 .LBB0_737
	v_lshlrev_b32_e32 v5, 1, v148
	s_add_i32 s4, 0, 0x19c00
	v_add_u32_e32 v2, s4, v5
	ds_read_u16 v29, v2 offset:6656
	ds_read_u16 v42, v2 offset:6784
	ds_read_u16 v43, v2 offset:6912
	ds_read_u16 v44, v2 offset:7040
	ds_read_u16 v45, v2 offset:7168
	ds_read_u16 v46, v2 offset:7296
	ds_read_u16 v47, v2 offset:7424
	ds_read_u16 v48, v2 offset:7552
	v_add_u32_e32 v3, s4, v148
	ds_read_u16 v49, v2 offset:7680
	ds_read_u16 v50, v2 offset:7808
	ds_read_u16 v51, v2 offset:7936
	ds_read_u16 v52, v2 offset:8064
	ds_read_u8 v1, v3 offset:9024
	ds_read_u8 v9, v3 offset:9152
	ds_read_u8 v0, v3 offset:9088
	ds_read_u8 v8, v3 offset:8960
	ds_read_u16 v59, v2 offset:1536
	ds_read_u16 v12, v2 offset:3584
	ds_read_u16 v62, v2 offset:1664
	ds_read_u16 v13, v2 offset:3712
	ds_read_u16 v65, v2 offset:1792
	ds_read_u16 v14, v2 offset:3840
	ds_read_u16 v15, v2 offset:3968
	ds_read_u16 v68, v2 offset:1920
	ds_read_u16 v69, v2 offset:6144
	ds_read_u16 v70, v2 offset:6272
	ds_read_u16 v71, v2 offset:6400
	ds_read_u16 v72, v2 offset:6528
	ds_read_u16 v73, v2 offset:5632
	ds_read_u16 v75, v2 offset:5760
	ds_read_u16 v77, v2 offset:5888
	ds_read_u16 v79, v2 offset:6016
	s_add_i32 s4, 0, 0x1c4c0
	v_mov_b32_e32 v7, s4
	s_add_i32 s4, 0, 0x1c4d0
	v_mov_b32_e32 v3, s4
	s_add_i32 s4, 0, 0x1c4e0
	v_mov_b32_e32 v10, s4
	s_add_i32 s4, 0, 0x1c4f0
	v_mov_b32_e32 v11, s4
	ds_read_b32 v2, v7
	ds_read_b32 v3, v3
	ds_read_b32 v10, v10
	ds_read_b32 v11, v11
	v_and_b32_e32 v7, 1, v128
	v_lshrrev_b32_e32 v16, 1, v128
	v_cmp_eq_u32_e64 s[6:7], 0, v7
	v_and_b32_e32 v7, 50, v128
	v_and_b32_e32 v5, 8, v5
	v_and_b32_e32 v16, 4, v16
	v_or3_b32 v53, v16, v7, v5
	v_and_b32_e32 v5, 32, v128
	v_and_b32_e32 v7, 31, v128
	s_mov_b32 s13, 0
	v_mul_u32_u24_e32 v54, 0x50, v148
	v_mul_u32_u24_e32 v55, 48, v5
	v_mul_u32_u24_e32 v56, 48, v7
	v_mov_b32_e32 v5, v4
	v_mov_b32_e32 v7, v6
	s_mov_b32 s12, 0x3b808081
	s_waitcnt lgkmcnt(0)
	s_setprio 2
	s_branch .LBB0_725

.LBB0_736:
	s_setprio 0
	s_mov_b64 s[46:47], 0

.LBB0_738:
	s_and_b64 vcc, exec, s[4:5]
	s_cbranch_vccz .LBB0_753
	v_lshlrev_b32_e32 v5, 1, v148
	s_add_i32 s4, 0, 0x19c00
	v_add_u32_e32 v2, s4, v5
	ds_read_u16 v40, v2 offset:6656
	ds_read_u16 v41, v2 offset:6784
	ds_read_u16 v42, v2 offset:6912
	ds_read_u16 v43, v2 offset:7040
	ds_read_u16 v44, v2 offset:7168
	ds_read_u16 v45, v2 offset:7296
	ds_read_u16 v46, v2 offset:7424
	ds_read_u16 v47, v2 offset:7552
	v_add_u32_e32 v3, s4, v148
	ds_read_u16 v48, v2 offset:7680
	ds_read_u16 v49, v2 offset:7808
	ds_read_u16 v50, v2 offset:7936
	ds_read_u16 v51, v2 offset:8064
	ds_read_u8 v1, v3 offset:8768
	ds_read_u8 v9, v3 offset:8896
	ds_read_u8 v0, v3 offset:8832
	ds_read_u8 v8, v3 offset:8704
	ds_read_u16 v58, v2 offset:1024
	ds_read_u16 v12, v2 offset:3072
	ds_read_u16 v61, v2 offset:1152
	ds_read_u16 v13, v2 offset:3200
	ds_read_u16 v64, v2 offset:1280
	ds_read_u16 v14, v2 offset:3328
	ds_read_u16 v15, v2 offset:3456
	ds_read_u16 v67, v2 offset:1408
	ds_read_u16 v68, v2 offset:6144
	ds_read_u16 v69, v2 offset:6272
	ds_read_u16 v70, v2 offset:6400
	ds_read_u16 v71, v2 offset:6528
	ds_read_u16 v72, v2 offset:5120
	ds_read_u16 v74, v2 offset:5248
	ds_read_u16 v76, v2 offset:5376
	ds_read_u16 v78, v2 offset:5504
	s_add_i32 s4, 0, 0x1c480
	v_mov_b32_e32 v7, s4
	s_add_i32 s4, 0, 0x1c490
	v_mov_b32_e32 v3, s4
	s_add_i32 s4, 0, 0x1c4a0
	v_mov_b32_e32 v10, s4
	s_add_i32 s4, 0, 0x1c4b0
	v_mov_b32_e32 v11, s4
	ds_read_b32 v2, v7
	ds_read_b32 v3, v3
	ds_read_b32 v10, v10
	ds_read_b32 v11, v11
	v_and_b32_e32 v7, 1, v128
	v_lshrrev_b32_e32 v16, 1, v128
	v_cmp_eq_u32_e64 s[6:7], 0, v7
	v_and_b32_e32 v7, 50, v128
	v_and_b32_e32 v5, 8, v5
	v_and_b32_e32 v16, 4, v16
	v_or3_b32 v52, v16, v7, v5
	v_and_b32_e32 v5, 32, v128
	v_and_b32_e32 v7, 31, v128
	s_mov_b32 s13, 0
	v_mul_u32_u24_e32 v53, 0x50, v148
	v_mul_u32_u24_e32 v54, 48, v5
	v_mul_u32_u24_e32 v55, 48, v7
	v_mov_b32_e32 v5, v4
	v_mov_b32_e32 v7, v6
	s_mov_b32 s12, 0x3b808081
	s_waitcnt lgkmcnt(0)
	s_setprio 2
	s_branch .LBB0_742

.LBB0_753:
	s_setprio 0
	s_mov_b64 s[4:5], 0
.LBB0_754:
	s_and_b64 vcc, exec, s[4:5]
	s_cbranch_vccz .LBB0_769
	v_lshlrev_b32_e32 v5, 1, v148
	s_add_i32 s4, 0, 0x19c00
	v_add_u32_e32 v2, s4, v5
	ds_read_u16 v40, v2 offset:6656
	ds_read_u16 v41, v2 offset:6784
	ds_read_u16 v42, v2 offset:6912
	ds_read_u16 v43, v2 offset:7040
	ds_read_u16 v44, v2 offset:7168
	ds_read_u16 v45, v2 offset:7296
	ds_read_u16 v46, v2 offset:7424
	ds_read_u16 v47, v2 offset:7552
	v_add_u32_e32 v3, s4, v148
	ds_read_u16 v48, v2 offset:7680
	ds_read_u16 v49, v2 offset:7808
	ds_read_u16 v50, v2 offset:7936
	ds_read_u16 v51, v2 offset:8064
	ds_read_u8 v1, v3 offset:8512
	ds_read_u8 v9, v3 offset:8640
	ds_read_u8 v0, v3 offset:8576
	ds_read_u8 v8, v3 offset:8448
	ds_read_u16 v58, v2 offset:512
	ds_read_u16 v12, v2 offset:2560
	ds_read_u16 v61, v2 offset:640
	ds_read_u16 v13, v2 offset:2688
	ds_read_u16 v64, v2 offset:768
	ds_read_u16 v14, v2 offset:2816
	ds_read_u16 v15, v2 offset:2944
	ds_read_u16 v67, v2 offset:896
	ds_read_u16 v68, v2 offset:6144
	ds_read_u16 v69, v2 offset:6272
	ds_read_u16 v70, v2 offset:6400
	ds_read_u16 v71, v2 offset:6528
	ds_read_u16 v72, v2 offset:4608
	ds_read_u16 v74, v2 offset:4736
	ds_read_u16 v76, v2 offset:4864
	ds_read_u16 v78, v2 offset:4992
	s_add_i32 s4, 0, 0x1c440
	v_mov_b32_e32 v7, s4
	s_add_i32 s4, 0, 0x1c450
	v_mov_b32_e32 v3, s4
	s_add_i32 s4, 0, 0x1c460
	v_mov_b32_e32 v10, s4
	s_add_i32 s4, 0, 0x1c470
	v_mov_b32_e32 v11, s4
	ds_read_b32 v2, v7
	ds_read_b32 v3, v3
	ds_read_b32 v10, v10
	ds_read_b32 v11, v11
	v_and_b32_e32 v7, 1, v128
	v_lshrrev_b32_e32 v16, 1, v128
	v_cmp_eq_u32_e64 s[6:7], 0, v7
	v_and_b32_e32 v7, 50, v128
	v_and_b32_e32 v5, 8, v5
	v_and_b32_e32 v16, 4, v16
	v_or3_b32 v52, v16, v7, v5
	v_and_b32_e32 v5, 32, v128
	v_and_b32_e32 v7, 31, v128
	s_mov_b32 s13, 0
	v_mul_u32_u24_e32 v53, 0x50, v148
	v_mul_u32_u24_e32 v54, 48, v5
	v_mul_u32_u24_e32 v55, 48, v7
	v_mov_b32_e32 v5, v4
	v_mov_b32_e32 v7, v6
	s_mov_b32 s12, 0x3b808081
	s_waitcnt lgkmcnt(0)
	s_setprio 2
	s_branch .LBB0_758

.LBB0_770:
	s_and_b64 vcc, exec, s[4:5]
	s_cbranch_vccz .LBB0_812
	s_cmp_gt_i32 s70, 2
	s_mov_b64 s[4:5], -1
	s_cbranch_scc0 .LBB0_810
	s_cmp_gt_i32 s70, 3
	v_and_b32_e32 v42, 3, v128
	s_cbranch_scc0 .LBB0_788
	s_add_i32 s4, 0, 0x19c00
	v_lshl_add_u32 v2, v148, 1, s4
	ds_read_u16 v43, v2 offset:6656
	ds_read_u16 v44, v2 offset:6784
	ds_read_u16 v45, v2 offset:6912
	ds_read_u16 v46, v2 offset:7040
	ds_read_u16 v47, v2 offset:7168
	ds_read_u16 v48, v2 offset:7296
	ds_read_u16 v49, v2 offset:7424
	ds_read_u16 v50, v2 offset:7552
	v_add_u32_e32 v3, s4, v148
	ds_read_u16 v51, v2 offset:7680
	ds_read_u16 v52, v2 offset:7808
	ds_read_u16 v53, v2 offset:7936
	ds_read_u16 v54, v2 offset:8064
	ds_read_u8 v1, v3 offset:8256
	ds_read_u8 v9, v3 offset:8384
	ds_read_u8 v0, v3 offset:8320
	ds_read_u8 v8, v3 offset:8192
	ds_read_u16 v63, v2
	ds_read_u16 v12, v2 offset:2048
	ds_read_u16 v66, v2 offset:128
	ds_read_u16 v13, v2 offset:2176
	ds_read_u16 v69, v2 offset:256
	ds_read_u16 v14, v2 offset:2304
	ds_read_u16 v15, v2 offset:2432
	ds_read_u16 v73, v2 offset:384
	ds_read_u16 v74, v2 offset:6144
	ds_read_u16 v75, v2 offset:6272
	ds_read_u16 v76, v2 offset:6400
	ds_read_u16 v77, v2 offset:6528
	ds_read_u16 v78, v2 offset:4096
	ds_read_u16 v79, v2 offset:4224
	ds_read_u16 v80, v2 offset:4352
	ds_read_u16 v82, v2 offset:4480
	s_add_i32 s4, 0, 0x1c400
	v_mov_b32_e32 v5, s4
	s_add_i32 s4, 0, 0x1c410
	v_mov_b32_e32 v3, s4
	s_add_i32 s4, 0, 0x1c420
	v_mov_b32_e32 v7, s4
	s_add_i32 s4, 0, 0x1c430
	v_mov_b32_e32 v11, s4
	ds_read_b32 v2, v5
	ds_read_b32 v3, v3
	ds_read_b32 v10, v7
	ds_read_b32 v11, v11
	v_and_b32_e32 v16, 1, v128
	v_bfe_u32 v5, v128, 2, 1
	v_lshrrev_b32_e32 v7, 1, v148
	v_cmp_eq_u32_e64 s[6:7], 0, v16
	v_and_b32_e32 v16, 48, v128
	v_and_or_b32 v55, v7, 12, v42
	v_lshl_or_b32 v16, v5, 3, v16
	v_and_or_b32 v56, v55, 6, v16
	v_and_b32_e32 v16, 31, v128
	v_and_b32_e32 v17, 32, v128
	s_mov_b32 s11, 0
	v_mul_u32_u24_e32 v57, 0x50, v148
	v_mul_u32_u24_e32 v58, 48, v17
	v_mul_u32_u24_e32 v59, 48, v16
	v_and_b32_e32 v60, 16, v7
	v_lshlrev_b32_e32 v61, 7, v5
	v_mov_b32_e32 v5, v4
	v_mov_b32_e32 v7, v6
	s_mov_b32 s10, 0x3b808081
	s_waitcnt lgkmcnt(0)
	s_setprio 2
	s_branch .LBB0_776
